# v2 plus plain (not nt) stores of the converted bf16 weights
# baseline (speedup 1.0000x reference)
.LBB0_312:
	s_waitcnt vmcnt(0)
	v_pk_mul_f32 v[2:3], v[2:3], v[112:113] op_sel_hi:[1,0]
	ds_write2_b32 v125, v2, v3 offset1:1
	v_pk_mul_f32 v[2:3], v[4:5], v[112:113] op_sel_hi:[1,0]
	ds_write2_b32 v125, v2, v3 offset0:2 offset1:3
	v_pk_mul_f32 v[2:3], v[6:7], v[110:111] op_sel_hi:[1,0]
	ds_write2_b32 v147, v2, v3 offset1:1
	v_pk_mul_f32 v[2:3], v[8:9], v[110:111] op_sel_hi:[1,0]
	ds_write2_b32 v146, v2, v3 offset1:1
	v_pk_mul_f32 v[2:3], v[10:11], v[118:119] op_sel_hi:[1,0]
	ds_write2_b32 v145, v2, v3 offset1:1
	v_pk_mul_f32 v[2:3], v[12:13], v[118:119] op_sel_hi:[1,0]
	ds_write2_b32 v144, v2, v3 offset1:1
	v_pk_mul_f32 v[2:3], v[14:15], v[114:115] op_sel_hi:[1,0]
	ds_write2_b32 v143, v2, v3 offset1:1
	v_pk_mul_f32 v[2:3], v[16:17], v[114:115] op_sel_hi:[1,0]
	ds_write2_b32 v141, v2, v3 offset1:1
	v_pk_mul_f32 v[2:3], v[18:19], v[122:123] op_sel_hi:[1,0]
	ds_write2_b32 v139, v2, v3 offset1:1
	v_pk_mul_f32 v[2:3], v[20:21], v[122:123] op_sel_hi:[1,0]
	ds_write2_b32 v137, v2, v3 offset1:1
	v_pk_mul_f32 v[2:3], v[22:23], v[120:121] op_sel_hi:[1,0]
	ds_write2_b32 v135, v2, v3 offset1:1
	v_pk_mul_f32 v[2:3], v[24:25], v[120:121] op_sel_hi:[1,0]
	ds_write2_b32 v133, v2, v3 offset1:1
	v_pk_mul_f32 v[2:3], v[26:27], v[126:127] op_sel_hi:[1,0]
	ds_write2_b32 v131, v2, v3 offset1:1
	v_pk_mul_f32 v[2:3], v[28:29], v[126:127] op_sel_hi:[1,0]
	ds_write2_b32 v129, v2, v3 offset1:1
	v_pk_mul_f32 v[2:3], v[30:31], v[124:125] op_sel_hi:[1,0]
	ds_write2_b32 v127, v2, v3 offset1:1
	v_pk_mul_f32 v[2:3], v[32:33], v[124:125] op_sel_hi:[1,0]
	ds_write2_b32 v109, v2, v3 offset1:1
	v_pk_mul_f32 v[2:3], v[34:35], v[130:131] op_sel_hi:[1,0]
	ds_write2_b32 v105, v2, v3 offset1:1
	v_pk_mul_f32 v[2:3], v[36:37], v[130:131] op_sel_hi:[1,0]
	ds_write2_b32 v103, v2, v3 offset1:1
	v_pk_mul_f32 v[2:3], v[38:39], v[128:129] op_sel_hi:[1,0]
	ds_write2_b32 v101, v2, v3 offset1:1
	v_pk_mul_f32 v[2:3], v[40:41], v[128:129] op_sel_hi:[1,0]
	ds_write2_b32 v99, v2, v3 offset1:1
	v_pk_mul_f32 v[2:3], v[42:43], v[134:135] op_sel_hi:[1,0]
	ds_write2_b32 v97, v2, v3 offset1:1
	v_pk_mul_f32 v[2:3], v[44:45], v[134:135] op_sel_hi:[1,0]
	ds_write2_b32 v95, v2, v3 offset1:1
	v_pk_mul_f32 v[2:3], v[46:47], v[132:133] op_sel_hi:[1,0]
	ds_write2_b32 v93, v2, v3 offset1:1
	v_pk_mul_f32 v[2:3], v[48:49], v[132:133] op_sel_hi:[1,0]
	ds_write2_b32 v91, v2, v3 offset1:1
	v_pk_mul_f32 v[2:3], v[50:51], v[138:139] op_sel_hi:[1,0]
	ds_write2_b32 v89, v2, v3 offset1:1
	v_pk_mul_f32 v[2:3], v[52:53], v[138:139] op_sel_hi:[1,0]
	ds_write2_b32 v85, v2, v3 offset1:1
	v_pk_mul_f32 v[2:3], v[54:55], v[136:137] op_sel_hi:[1,0]
	ds_write2_b32 v83, v2, v3 offset1:1
	v_pk_mul_f32 v[2:3], v[56:57], v[136:137] op_sel_hi:[1,0]
	ds_write2_b32 v81, v2, v3 offset1:1
	v_pk_mul_f32 v[2:3], v[58:59], v[142:143] op_sel_hi:[1,0]
	ds_write2_b32 v79, v2, v3 offset1:1
	v_pk_mul_f32 v[2:3], v[60:61], v[142:143] op_sel_hi:[1,0]
	ds_write2_b32 v77, v2, v3 offset1:1
	v_pk_mul_f32 v[2:3], v[62:63], v[140:141] op_sel_hi:[1,0]
	ds_write2_b32 v75, v2, v3 offset1:1
	v_pk_mul_f32 v[2:3], v[64:65], v[140:141] op_sel_hi:[1,0]
	ds_write2_b32 v73, v2, v3 offset1:1
	s_waitcnt lgkmcnt(0)
	ds_read2_b32 v[2:3], v119 offset1:33
	v_ashrrev_i32_e32 v109, 31, v108
	s_waitcnt lgkmcnt(0)
	v_cvt_pk_bf16_f32 v2, v2, v3
	ds_read2_b32 v[4:5], v119 offset0:66 offset1:99
	v_lshl_add_u64 v[8:9], v[108:109], 1, v[106:107]
	v_mov_b32_e32 v105, v0
	s_waitcnt lgkmcnt(0)
	v_cvt_pk_bf16_f32 v3, v4, v5
	ds_read2_b32 v[4:5], v119 offset0:132 offset1:165
	v_lshl_add_u64 v[8:9], v[8:9], 0, v[104:105]
	v_mov_b32_e32 v89, v0
	s_waitcnt lgkmcnt(0)
	v_cvt_pk_bf16_f32 v4, v4, v5
	ds_read2_b32 v[6:7], v119 offset0:198 offset1:231
	s_waitcnt lgkmcnt(0)
	v_cvt_pk_bf16_f32 v5, v6, v7
	v_lshl_add_u64 v[10:11], v[8:9], 0, v[88:89]
	ds_read2_b32 v[6:7], v119 offset0:4 offset1:37
	global_store_dwordx4 v[10:11], v[2:5], off
	v_mov_b32_e32 v91, v0
	v_lshl_add_u64 v[10:11], v[8:9], 0, v[90:91]
	s_waitcnt lgkmcnt(0)
	v_cvt_pk_bf16_f32 v2, v6, v7
	ds_read2_b32 v[4:5], v119 offset0:70 offset1:103
	s_waitcnt lgkmcnt(0)
	v_cvt_pk_bf16_f32 v3, v4, v5
	ds_read2_b32 v[4:5], v119 offset0:136 offset1:169
	s_waitcnt lgkmcnt(0)
	v_cvt_pk_bf16_f32 v4, v4, v5
	ds_read2_b32 v[6:7], v119 offset0:202 offset1:235
	s_waitcnt lgkmcnt(0)
	v_cvt_pk_bf16_f32 v5, v6, v7
	ds_read2_b32 v[6:7], v119 offset0:8 offset1:41
	global_store_dwordx4 v[10:11], v[2:5], off
	v_mov_b32_e32 v93, v0
	v_lshl_add_u64 v[10:11], v[8:9], 0, v[92:93]
	s_waitcnt lgkmcnt(0)
	v_cvt_pk_bf16_f32 v2, v6, v7
	ds_read2_b32 v[4:5], v119 offset0:74 offset1:107
	s_waitcnt lgkmcnt(0)
	v_cvt_pk_bf16_f32 v3, v4, v5
	ds_read2_b32 v[4:5], v119 offset0:140 offset1:173
	s_waitcnt lgkmcnt(0)
	v_cvt_pk_bf16_f32 v4, v4, v5
	ds_read2_b32 v[6:7], v119 offset0:206 offset1:239
	s_waitcnt lgkmcnt(0)
	v_cvt_pk_bf16_f32 v5, v6, v7
	ds_read2_b32 v[6:7], v119 offset0:12 offset1:45
	global_store_dwordx4 v[10:11], v[2:5], off
	v_mov_b32_e32 v95, v0
	v_lshl_add_u64 v[10:11], v[8:9], 0, v[94:95]
	s_waitcnt lgkmcnt(0)
	v_cvt_pk_bf16_f32 v2, v6, v7
	ds_read2_b32 v[4:5], v119 offset0:78 offset1:111
	s_waitcnt lgkmcnt(0)
	v_cvt_pk_bf16_f32 v3, v4, v5
	ds_read2_b32 v[4:5], v119 offset0:144 offset1:177
	s_waitcnt lgkmcnt(0)
	v_cvt_pk_bf16_f32 v4, v4, v5
	ds_read2_b32 v[6:7], v119 offset0:210 offset1:243
	s_waitcnt lgkmcnt(0)
	v_cvt_pk_bf16_f32 v5, v6, v7
	ds_read2_b32 v[6:7], v119 offset0:16 offset1:49
	global_store_dwordx4 v[10:11], v[2:5], off
	v_mov_b32_e32 v97, v0
	v_lshl_add_u64 v[10:11], v[8:9], 0, v[96:97]
	s_waitcnt lgkmcnt(0)
	v_cvt_pk_bf16_f32 v2, v6, v7
	ds_read2_b32 v[4:5], v119 offset0:82 offset1:115
	s_waitcnt lgkmcnt(0)
	v_cvt_pk_bf16_f32 v3, v4, v5
	ds_read2_b32 v[4:5], v119 offset0:148 offset1:181
	s_waitcnt lgkmcnt(0)
	v_cvt_pk_bf16_f32 v4, v4, v5
	ds_read2_b32 v[6:7], v119 offset0:214 offset1:247
	s_waitcnt lgkmcnt(0)
	v_cvt_pk_bf16_f32 v5, v6, v7
	ds_read2_b32 v[6:7], v119 offset0:20 offset1:53
	global_store_dwordx4 v[10:11], v[2:5], off
	v_mov_b32_e32 v99, v0
	v_lshl_add_u64 v[10:11], v[8:9], 0, v[98:99]
	s_waitcnt lgkmcnt(0)
	v_cvt_pk_bf16_f32 v2, v6, v7
	ds_read2_b32 v[4:5], v119 offset0:86 offset1:119
	s_waitcnt lgkmcnt(0)
	v_cvt_pk_bf16_f32 v3, v4, v5
	ds_read2_b32 v[4:5], v119 offset0:152 offset1:185
	s_waitcnt lgkmcnt(0)
	v_cvt_pk_bf16_f32 v4, v4, v5
	ds_read2_b32 v[6:7], v119 offset0:218 offset1:251
	s_waitcnt lgkmcnt(0)
	v_cvt_pk_bf16_f32 v5, v6, v7
	ds_read2_b32 v[6:7], v119 offset0:24 offset1:57
	global_store_dwordx4 v[10:11], v[2:5], off
	v_mov_b32_e32 v101, v0
	v_lshl_add_u64 v[10:11], v[8:9], 0, v[100:101]
	s_waitcnt lgkmcnt(0)
	v_cvt_pk_bf16_f32 v2, v6, v7
	ds_read2_b32 v[4:5], v119 offset0:90 offset1:123
	s_waitcnt lgkmcnt(0)
	v_cvt_pk_bf16_f32 v3, v4, v5
	ds_read2_b32 v[4:5], v119 offset0:156 offset1:189
	s_waitcnt lgkmcnt(0)
	v_cvt_pk_bf16_f32 v4, v4, v5
	ds_read2_b32 v[6:7], v119 offset0:222 offset1:255
	s_waitcnt lgkmcnt(0)
	v_cvt_pk_bf16_f32 v5, v6, v7
	ds_read2_b32 v[6:7], v119 offset0:28 offset1:61
	global_store_dwordx4 v[10:11], v[2:5], off
	v_mov_b32_e32 v103, v0
	s_waitcnt lgkmcnt(0)
	v_cvt_pk_bf16_f32 v2, v6, v7
	ds_read2_b32 v[4:5], v119 offset0:94 offset1:127
	s_waitcnt lgkmcnt(0)
	v_cvt_pk_bf16_f32 v3, v4, v5
	ds_read2_b32 v[4:5], v119 offset0:160 offset1:193
	s_waitcnt lgkmcnt(0)
	v_cvt_pk_bf16_f32 v4, v4, v5
	ds_read2_b32 v[6:7], v87 offset0:98 offset1:131
	s_waitcnt lgkmcnt(0)
	v_cvt_pk_bf16_f32 v5, v6, v7
	v_lshl_add_u64 v[6:7], v[8:9], 0, v[102:103]
	global_store_dwordx4 v[6:7], v[2:5], off
	s_waitcnt lgkmcnt(0)

.LBB0_314:
	v_cmp_lt_i32_e32 vcc, s51, v113
	v_add_u32_e32 v147, 0x420, v125
	v_add_u32_e32 v146, 0x428, v125
	v_add_u32_e32 v145, 0x840, v125
	v_add_u32_e32 v144, 0x848, v125
	v_add_u32_e32 v143, 0xc60, v125
	v_add_u32_e32 v141, 0xc68, v125
	v_add_u32_e32 v139, 0x1080, v125
	v_add_u32_e32 v137, 0x1088, v125
	v_add_u32_e32 v135, 0x14a0, v125
	v_add_u32_e32 v133, 0x14a8, v125
	v_add_u32_e32 v131, 0x18c0, v125
	v_add_u32_e32 v129, 0x18c8, v125
	v_add_u32_e32 v127, 0x1ce0, v125
	v_add_u32_e32 v109, 0x1ce8, v125
	v_add_u32_e32 v105, 0x2100, v125
	v_add_u32_e32 v103, 0x2108, v125
	v_add_u32_e32 v101, 0x2520, v125
	v_add_u32_e32 v99, 0x2528, v125
	v_add_u32_e32 v97, 0x2940, v125
	v_add_u32_e32 v95, 0x2948, v125
	v_add_u32_e32 v93, 0x2d60, v125
	v_add_u32_e32 v91, 0x2d68, v125
	v_add_u32_e32 v89, 0x3180, v125
	v_add_u32_e32 v85, 0x3188, v125
	v_add_u32_e32 v83, 0x35a0, v125
	v_add_u32_e32 v81, 0x35a8, v125
	v_add_u32_e32 v79, 0x39c0, v125
	v_add_u32_e32 v77, 0x39c8, v125
	v_add_u32_e32 v75, 0x3de0, v125
	v_add_u32_e32 v73, 0x3de8, v125
	v_lshlrev_b32_e32 v104, 1, v68
	v_add_u32_e32 v87, 0x200, v119
	s_and_saveexec_b64 s[12:13], vcc
	s_xor_b64 s[38:39], exec, s[12:13]
	s_cbranch_execz .LBB0_316
	v_and_b32_e32 v106, 0x7fffff80, v123
	v_add_u32_e32 v2, 0xfffcbe00, v121
	v_and_b32_e32 v107, 0x7e0, v2
	v_or_b32_e32 v62, v106, v115
	v_lshlrev_b32_e32 v2, 2, v107
	v_mov_b32_e32 v3, v0
	v_mov_b32_e32 v63, v0
	v_or_b32_e32 v4, 8, v62
	v_mov_b32_e32 v5, v0
	v_or_b32_e32 v10, 16, v62
	v_mov_b32_e32 v11, v0
	v_or_b32_e32 v12, 24, v62
	v_mov_b32_e32 v13, v0
	v_or_b32_e32 v18, 32, v62
	v_mov_b32_e32 v19, v0
	v_or_b32_e32 v20, 40, v62
	v_mov_b32_e32 v21, v0
	v_or_b32_e32 v26, 48, v62
	v_mov_b32_e32 v27, v0
	v_or_b32_e32 v28, 56, v62
	v_mov_b32_e32 v29, v0
	v_or_b32_e32 v34, 64, v62
	v_mov_b32_e32 v35, v0
	v_or_b32_e32 v36, 0x48, v62
	v_mov_b32_e32 v37, v0
	v_or_b32_e32 v42, 0x50, v62
	v_mov_b32_e32 v43, v0
	v_or_b32_e32 v44, 0x58, v62
	v_mov_b32_e32 v45, v0
	v_or_b32_e32 v50, 0x60, v62
	v_mov_b32_e32 v51, v0
	v_or_b32_e32 v52, 0x68, v62
	v_mov_b32_e32 v53, v0
	v_lshl_add_u64 v[64:65], v[66:67], 0, v[2:3]
	v_lshlrev_b64 v[2:3], 13, v[62:63]
	v_lshlrev_b64 v[4:5], 13, v[4:5]
	v_lshlrev_b64 v[10:11], 13, v[10:11]
	v_lshlrev_b64 v[12:13], 13, v[12:13]
	v_lshlrev_b64 v[18:19], 13, v[18:19]
	v_lshlrev_b64 v[20:21], 13, v[20:21]
	v_lshlrev_b64 v[26:27], 13, v[26:27]
	v_lshlrev_b64 v[28:29], 13, v[28:29]
	v_lshlrev_b64 v[34:35], 13, v[34:35]
	v_lshlrev_b64 v[36:37], 13, v[36:37]
	v_lshlrev_b64 v[42:43], 13, v[42:43]
	v_lshlrev_b64 v[44:45], 13, v[44:45]
	v_lshlrev_b64 v[50:51], 13, v[50:51]
	v_lshlrev_b64 v[52:53], 13, v[52:53]
	v_lshl_add_u64 v[2:3], v[64:65], 0, v[2:3]
	v_lshl_add_u64 v[6:7], v[64:65], 0, v[4:5]
	v_lshl_add_u64 v[10:11], v[64:65], 0, v[10:11]
	v_lshl_add_u64 v[14:15], v[64:65], 0, v[12:13]
	v_lshl_add_u64 v[18:19], v[64:65], 0, v[18:19]
	v_lshl_add_u64 v[22:23], v[64:65], 0, v[20:21]
	v_lshl_add_u64 v[26:27], v[64:65], 0, v[26:27]
	v_lshl_add_u64 v[30:31], v[64:65], 0, v[28:29]
	v_lshl_add_u64 v[34:35], v[64:65], 0, v[34:35]
	v_lshl_add_u64 v[38:39], v[64:65], 0, v[36:37]
	v_lshl_add_u64 v[42:43], v[64:65], 0, v[42:43]
	v_lshl_add_u64 v[46:47], v[64:65], 0, v[44:45]
	v_lshl_add_u64 v[50:51], v[64:65], 0, v[50:51]
	v_lshl_add_u64 v[54:55], v[64:65], 0, v[52:53]
	global_load_dwordx4 v[2:5], v[2:3], off nt
	s_nop 0
	global_load_dwordx4 v[6:9], v[6:7], off nt
	s_nop 0
	global_load_dwordx4 v[10:13], v[10:11], off nt
	s_nop 0
	global_load_dwordx4 v[14:17], v[14:15], off nt
	s_nop 0
	global_load_dwordx4 v[18:21], v[18:19], off nt
	s_nop 0
	global_load_dwordx4 v[22:25], v[22:23], off nt
	s_nop 0
	global_load_dwordx4 v[26:29], v[26:27], off nt
	s_nop 0
	global_load_dwordx4 v[30:33], v[30:31], off nt
	s_nop 0
	global_load_dwordx4 v[34:37], v[34:35], off nt
	s_nop 0
	global_load_dwordx4 v[38:41], v[38:39], off nt
	s_nop 0
	global_load_dwordx4 v[42:45], v[42:43], off nt
	s_nop 0
	global_load_dwordx4 v[46:49], v[46:47], off nt
	s_nop 0
	global_load_dwordx4 v[50:53], v[50:51], off nt
	s_nop 0
	global_load_dwordx4 v[54:57], v[54:55], off nt
	v_or_b32_e32 v58, 0x70, v62
	v_mov_b32_e32 v59, v0
	v_lshlrev_b64 v[58:59], 13, v[58:59]
	v_lshl_add_u64 v[58:59], v[64:65], 0, v[58:59]
	v_or_b32_e32 v62, 0x78, v62
	global_load_dwordx4 v[58:61], v[58:59], off nt
	v_lshlrev_b64 v[62:63], 13, v[62:63]
	v_lshl_add_u64 v[62:63], v[64:65], 0, v[62:63]
	global_load_dwordx4 v[62:65], v[62:63], off nt
	s_waitcnt vmcnt(0)
	ds_write2_b32 v125, v2, v3 offset1:1
	ds_write2_b32 v125, v4, v5 offset0:2 offset1:3
	ds_write2_b32 v147, v6, v7 offset1:1
	ds_write2_b32 v146, v8, v9 offset1:1
	ds_write2_b32 v145, v10, v11 offset1:1
	ds_write2_b32 v144, v12, v13 offset1:1
	ds_write2_b32 v143, v14, v15 offset1:1
	ds_write2_b32 v141, v16, v17 offset1:1
	ds_write2_b32 v139, v18, v19 offset1:1
	ds_write2_b32 v137, v20, v21 offset1:1
	ds_write2_b32 v135, v22, v23 offset1:1
	ds_write2_b32 v133, v24, v25 offset1:1
	ds_write2_b32 v131, v26, v27 offset1:1
	ds_write2_b32 v129, v28, v29 offset1:1
	ds_write2_b32 v127, v30, v31 offset1:1
	ds_write2_b32 v109, v32, v33 offset1:1
	ds_write2_b32 v105, v34, v35 offset1:1
	ds_write2_b32 v103, v36, v37 offset1:1
	ds_write2_b32 v101, v38, v39 offset1:1
	ds_write2_b32 v99, v40, v41 offset1:1
	ds_write2_b32 v97, v42, v43 offset1:1
	ds_write2_b32 v95, v44, v45 offset1:1
	ds_write2_b32 v93, v46, v47 offset1:1
	ds_write2_b32 v91, v48, v49 offset1:1
	ds_write2_b32 v89, v50, v51 offset1:1
	ds_write2_b32 v85, v52, v53 offset1:1
	ds_write2_b32 v83, v54, v55 offset1:1
	ds_write2_b32 v81, v56, v57 offset1:1
	ds_write2_b32 v79, v58, v59 offset1:1
	ds_write2_b32 v77, v60, v61 offset1:1
	ds_write2_b32 v75, v62, v63 offset1:1
	ds_write2_b32 v73, v64, v65 offset1:1
	s_waitcnt lgkmcnt(0)
	v_lshlrev_b32_e32 v6, 13, v107
	v_mov_b32_e32 v7, v0
	ds_read2_b32 v[2:3], v119 offset1:33
	v_lshl_add_u64 v[6:7], s[20:21], 0, v[6:7]
	v_lshlrev_b32_e32 v10, 1, v106
	v_mov_b32_e32 v11, v0
	s_waitcnt lgkmcnt(0)
	v_cvt_pk_bf16_f32 v2, v2, v3
	ds_read2_b32 v[4:5], v119 offset0:66 offset1:99
	v_lshl_add_u64 v[6:7], v[6:7], 0, v[10:11]
	v_mov_b32_e32 v105, v0
	s_waitcnt lgkmcnt(0)
	v_cvt_pk_bf16_f32 v3, v4, v5
	ds_read2_b32 v[4:5], v119 offset0:132 offset1:165
	v_lshl_add_u64 v[6:7], v[6:7], 0, v[104:105]
	v_mov_b32_e32 v73, v0
	s_waitcnt lgkmcnt(0)
	v_cvt_pk_bf16_f32 v4, v4, v5
	ds_read2_b32 v[8:9], v119 offset0:198 offset1:231
	s_waitcnt lgkmcnt(0)
	v_cvt_pk_bf16_f32 v5, v8, v9
	v_lshl_add_u64 v[10:11], v[6:7], 0, v[72:73]
	ds_read2_b32 v[8:9], v119 offset0:4 offset1:37
	global_store_dwordx4 v[10:11], v[2:5], off
	v_mov_b32_e32 v75, v0
	v_lshl_add_u64 v[10:11], v[6:7], 0, v[74:75]
	s_waitcnt lgkmcnt(0)
	v_cvt_pk_bf16_f32 v2, v8, v9
	ds_read2_b32 v[4:5], v119 offset0:70 offset1:103
	s_waitcnt lgkmcnt(0)
	v_cvt_pk_bf16_f32 v3, v4, v5
	ds_read2_b32 v[4:5], v119 offset0:136 offset1:169
	s_waitcnt lgkmcnt(0)
	v_cvt_pk_bf16_f32 v4, v4, v5
	ds_read2_b32 v[8:9], v119 offset0:202 offset1:235
	s_waitcnt lgkmcnt(0)
	v_cvt_pk_bf16_f32 v5, v8, v9
	ds_read2_b32 v[8:9], v119 offset0:8 offset1:41
	global_store_dwordx4 v[10:11], v[2:5], off
	v_mov_b32_e32 v77, v0
	v_lshl_add_u64 v[10:11], v[6:7], 0, v[76:77]
	s_waitcnt lgkmcnt(0)
	v_cvt_pk_bf16_f32 v2, v8, v9
	ds_read2_b32 v[4:5], v119 offset0:74 offset1:107
	s_waitcnt lgkmcnt(0)
	v_cvt_pk_bf16_f32 v3, v4, v5
	ds_read2_b32 v[4:5], v119 offset0:140 offset1:173
	s_waitcnt lgkmcnt(0)
	v_cvt_pk_bf16_f32 v4, v4, v5
	ds_read2_b32 v[8:9], v119 offset0:206 offset1:239
	s_waitcnt lgkmcnt(0)
	v_cvt_pk_bf16_f32 v5, v8, v9
	ds_read2_b32 v[8:9], v119 offset0:12 offset1:45
	global_store_dwordx4 v[10:11], v[2:5], off
	v_mov_b32_e32 v79, v0
	v_lshl_add_u64 v[10:11], v[6:7], 0, v[78:79]
	s_waitcnt lgkmcnt(0)
	v_cvt_pk_bf16_f32 v2, v8, v9
	ds_read2_b32 v[4:5], v119 offset0:78 offset1:111
	s_waitcnt lgkmcnt(0)
	v_cvt_pk_bf16_f32 v3, v4, v5
	ds_read2_b32 v[4:5], v119 offset0:144 offset1:177
	s_waitcnt lgkmcnt(0)
	v_cvt_pk_bf16_f32 v4, v4, v5
	ds_read2_b32 v[8:9], v119 offset0:210 offset1:243
	s_waitcnt lgkmcnt(0)
	v_cvt_pk_bf16_f32 v5, v8, v9
	ds_read2_b32 v[8:9], v119 offset0:16 offset1:49
	global_store_dwordx4 v[10:11], v[2:5], off
	v_mov_b32_e32 v81, v0
	v_lshl_add_u64 v[10:11], v[6:7], 0, v[80:81]
	s_waitcnt lgkmcnt(0)
	v_cvt_pk_bf16_f32 v2, v8, v9
	ds_read2_b32 v[4:5], v119 offset0:82 offset1:115
	s_waitcnt lgkmcnt(0)
	v_cvt_pk_bf16_f32 v3, v4, v5
	ds_read2_b32 v[4:5], v119 offset0:148 offset1:181
	s_waitcnt lgkmcnt(0)
	v_cvt_pk_bf16_f32 v4, v4, v5
	ds_read2_b32 v[8:9], v119 offset0:214 offset1:247
	s_waitcnt lgkmcnt(0)
	v_cvt_pk_bf16_f32 v5, v8, v9
	ds_read2_b32 v[8:9], v119 offset0:20 offset1:53
	global_store_dwordx4 v[10:11], v[2:5], off
	v_mov_b32_e32 v83, v0
	v_lshl_add_u64 v[10:11], v[6:7], 0, v[82:83]
	s_waitcnt lgkmcnt(0)
	v_cvt_pk_bf16_f32 v2, v8, v9
	ds_read2_b32 v[4:5], v119 offset0:86 offset1:119
	s_waitcnt lgkmcnt(0)
	v_cvt_pk_bf16_f32 v3, v4, v5
	ds_read2_b32 v[4:5], v119 offset0:152 offset1:185
	s_waitcnt lgkmcnt(0)
	v_cvt_pk_bf16_f32 v4, v4, v5
	ds_read2_b32 v[8:9], v119 offset0:218 offset1:251
	s_waitcnt lgkmcnt(0)
	v_cvt_pk_bf16_f32 v5, v8, v9
	ds_read2_b32 v[8:9], v119 offset0:24 offset1:57
	global_store_dwordx4 v[10:11], v[2:5], off
	v_mov_b32_e32 v85, v0
	v_lshl_add_u64 v[10:11], v[6:7], 0, v[84:85]
	s_waitcnt lgkmcnt(0)
	v_cvt_pk_bf16_f32 v2, v8, v9
	ds_read2_b32 v[4:5], v119 offset0:90 offset1:123
	s_waitcnt lgkmcnt(0)
	v_cvt_pk_bf16_f32 v3, v4, v5
	ds_read2_b32 v[4:5], v119 offset0:156 offset1:189
	s_waitcnt lgkmcnt(0)
	v_cvt_pk_bf16_f32 v4, v4, v5
	ds_read2_b32 v[8:9], v119 offset0:222 offset1:255
	s_waitcnt lgkmcnt(0)
	v_cvt_pk_bf16_f32 v5, v8, v9
	ds_read2_b32 v[8:9], v119 offset0:28 offset1:61
	global_store_dwordx4 v[10:11], v[2:5], off
	s_waitcnt lgkmcnt(0)
	s_nop 0
	v_cvt_pk_bf16_f32 v2, v8, v9
	ds_read2_b32 v[4:5], v119 offset0:94 offset1:127
	s_waitcnt lgkmcnt(0)
	v_cvt_pk_bf16_f32 v3, v4, v5
	ds_read2_b32 v[4:5], v119 offset0:160 offset1:193
	s_waitcnt lgkmcnt(0)
	v_cvt_pk_bf16_f32 v4, v4, v5
	ds_read2_b32 v[8:9], v87 offset0:98 offset1:131
	v_mov_b32_e32 v87, v0
	v_lshl_add_u64 v[6:7], v[6:7], 0, v[86:87]
	s_waitcnt lgkmcnt(0)
	v_cvt_pk_bf16_f32 v5, v8, v9
	global_store_dwordx4 v[6:7], v[2:5], off
	s_waitcnt lgkmcnt(0)

.LBB0_360:
	s_waitcnt vmcnt(0)
	v_pk_mul_f32 v[2:3], v[2:3], v[112:113] op_sel_hi:[1,0]
	ds_write2_b32 v119, v2, v3 offset1:1
	v_pk_mul_f32 v[2:3], v[4:5], v[112:113] op_sel_hi:[1,0]
	ds_write2_b32 v119, v2, v3 offset0:2 offset1:3
	v_pk_mul_f32 v[2:3], v[6:7], v[110:111] op_sel_hi:[1,0]
	ds_write2_b32 v144, v2, v3 offset1:1
	v_pk_mul_f32 v[2:3], v[8:9], v[110:111] op_sel_hi:[1,0]
	ds_write2_b32 v143, v2, v3 offset1:1
	v_pk_mul_f32 v[2:3], v[10:11], v[118:119] op_sel_hi:[1,0]
	ds_write2_b32 v141, v2, v3 offset1:1
	v_pk_mul_f32 v[2:3], v[12:13], v[118:119] op_sel_hi:[1,0]
	ds_write2_b32 v139, v2, v3 offset1:1
	v_pk_mul_f32 v[2:3], v[14:15], v[114:115] op_sel_hi:[1,0]
	ds_write2_b32 v137, v2, v3 offset1:1
	v_pk_mul_f32 v[2:3], v[16:17], v[114:115] op_sel_hi:[1,0]
	ds_write2_b32 v135, v2, v3 offset1:1
	v_pk_mul_f32 v[2:3], v[18:19], v[122:123] op_sel_hi:[1,0]
	ds_write2_b32 v133, v2, v3 offset1:1
	v_pk_mul_f32 v[2:3], v[20:21], v[122:123] op_sel_hi:[1,0]
	ds_write2_b32 v131, v2, v3 offset1:1
	v_pk_mul_f32 v[2:3], v[22:23], v[120:121] op_sel_hi:[1,0]
	ds_write2_b32 v129, v2, v3 offset1:1
	v_pk_mul_f32 v[2:3], v[24:25], v[120:121] op_sel_hi:[1,0]
	ds_write2_b32 v127, v2, v3 offset1:1
	v_pk_mul_f32 v[2:3], v[26:27], v[126:127] op_sel_hi:[1,0]
	ds_write2_b32 v125, v2, v3 offset1:1
	v_pk_mul_f32 v[2:3], v[28:29], v[126:127] op_sel_hi:[1,0]
	ds_write2_b32 v123, v2, v3 offset1:1
	v_pk_mul_f32 v[2:3], v[30:31], v[124:125] op_sel_hi:[1,0]
	ds_write2_b32 v121, v2, v3 offset1:1
	v_pk_mul_f32 v[2:3], v[32:33], v[124:125] op_sel_hi:[1,0]
	ds_write2_b32 v109, v2, v3 offset1:1
	v_pk_mul_f32 v[2:3], v[34:35], v[130:131] op_sel_hi:[1,0]
	ds_write2_b32 v105, v2, v3 offset1:1
	v_pk_mul_f32 v[2:3], v[36:37], v[130:131] op_sel_hi:[1,0]
	ds_write2_b32 v103, v2, v3 offset1:1
	v_pk_mul_f32 v[2:3], v[38:39], v[128:129] op_sel_hi:[1,0]
	ds_write2_b32 v101, v2, v3 offset1:1
	v_pk_mul_f32 v[2:3], v[40:41], v[128:129] op_sel_hi:[1,0]
	ds_write2_b32 v99, v2, v3 offset1:1
	v_pk_mul_f32 v[2:3], v[42:43], v[134:135] op_sel_hi:[1,0]
	ds_write2_b32 v97, v2, v3 offset1:1
	v_pk_mul_f32 v[2:3], v[44:45], v[134:135] op_sel_hi:[1,0]
	ds_write2_b32 v95, v2, v3 offset1:1
	v_pk_mul_f32 v[2:3], v[46:47], v[132:133] op_sel_hi:[1,0]
	ds_write2_b32 v93, v2, v3 offset1:1
	v_pk_mul_f32 v[2:3], v[48:49], v[132:133] op_sel_hi:[1,0]
	ds_write2_b32 v91, v2, v3 offset1:1
	v_pk_mul_f32 v[2:3], v[50:51], v[138:139] op_sel_hi:[1,0]
	ds_write2_b32 v89, v2, v3 offset1:1
	v_pk_mul_f32 v[2:3], v[52:53], v[138:139] op_sel_hi:[1,0]
	ds_write2_b32 v85, v2, v3 offset1:1
	v_pk_mul_f32 v[2:3], v[54:55], v[136:137] op_sel_hi:[1,0]
	ds_write2_b32 v83, v2, v3 offset1:1
	v_pk_mul_f32 v[2:3], v[56:57], v[136:137] op_sel_hi:[1,0]
	ds_write2_b32 v81, v2, v3 offset1:1
	v_pk_mul_f32 v[2:3], v[58:59], v[142:143] op_sel_hi:[1,0]
	ds_write2_b32 v79, v2, v3 offset1:1
	v_pk_mul_f32 v[2:3], v[60:61], v[142:143] op_sel_hi:[1,0]
	ds_write2_b32 v77, v2, v3 offset1:1
	v_pk_mul_f32 v[2:3], v[62:63], v[140:141] op_sel_hi:[1,0]
	ds_write2_b32 v75, v2, v3 offset1:1
	v_pk_mul_f32 v[2:3], v[64:65], v[140:141] op_sel_hi:[1,0]
	ds_write2_b32 v73, v2, v3 offset1:1
	s_waitcnt lgkmcnt(0)
	ds_read2_b32 v[2:3], v1 offset1:33
	v_ashrrev_i32_e32 v109, 31, v108
	s_waitcnt lgkmcnt(0)
	v_cvt_pk_bf16_f32 v2, v2, v3
	ds_read2_b32 v[4:5], v1 offset0:66 offset1:99
	v_lshl_add_u64 v[8:9], v[108:109], 1, v[106:107]
	v_mov_b32_e32 v105, v0
	s_waitcnt lgkmcnt(0)
	v_cvt_pk_bf16_f32 v3, v4, v5
	ds_read2_b32 v[4:5], v1 offset0:132 offset1:165
	v_lshl_add_u64 v[8:9], v[8:9], 0, v[104:105]
	v_mov_b32_e32 v89, v0
	s_waitcnt lgkmcnt(0)
	v_cvt_pk_bf16_f32 v4, v4, v5
	ds_read2_b32 v[6:7], v1 offset0:198 offset1:231
	s_waitcnt lgkmcnt(0)
	v_cvt_pk_bf16_f32 v5, v6, v7
	v_lshl_add_u64 v[10:11], v[8:9], 0, v[88:89]
	ds_read2_b32 v[6:7], v1 offset0:4 offset1:37
	global_store_dwordx4 v[10:11], v[2:5], off
	v_mov_b32_e32 v91, v0
	v_lshl_add_u64 v[10:11], v[8:9], 0, v[90:91]
	s_waitcnt lgkmcnt(0)
	v_cvt_pk_bf16_f32 v2, v6, v7
	ds_read2_b32 v[4:5], v1 offset0:70 offset1:103
	s_waitcnt lgkmcnt(0)
	v_cvt_pk_bf16_f32 v3, v4, v5
	ds_read2_b32 v[4:5], v1 offset0:136 offset1:169
	s_waitcnt lgkmcnt(0)
	v_cvt_pk_bf16_f32 v4, v4, v5
	ds_read2_b32 v[6:7], v1 offset0:202 offset1:235
	s_waitcnt lgkmcnt(0)
	v_cvt_pk_bf16_f32 v5, v6, v7
	ds_read2_b32 v[6:7], v1 offset0:8 offset1:41
	global_store_dwordx4 v[10:11], v[2:5], off
	v_mov_b32_e32 v93, v0
	v_lshl_add_u64 v[10:11], v[8:9], 0, v[92:93]
	s_waitcnt lgkmcnt(0)
	v_cvt_pk_bf16_f32 v2, v6, v7
	ds_read2_b32 v[4:5], v1 offset0:74 offset1:107
	s_waitcnt lgkmcnt(0)
	v_cvt_pk_bf16_f32 v3, v4, v5
	ds_read2_b32 v[4:5], v1 offset0:140 offset1:173
	s_waitcnt lgkmcnt(0)
	v_cvt_pk_bf16_f32 v4, v4, v5
	ds_read2_b32 v[6:7], v1 offset0:206 offset1:239
	s_waitcnt lgkmcnt(0)
	v_cvt_pk_bf16_f32 v5, v6, v7
	ds_read2_b32 v[6:7], v1 offset0:12 offset1:45
	global_store_dwordx4 v[10:11], v[2:5], off
	v_mov_b32_e32 v95, v0
	v_lshl_add_u64 v[10:11], v[8:9], 0, v[94:95]
	s_waitcnt lgkmcnt(0)
	v_cvt_pk_bf16_f32 v2, v6, v7
	ds_read2_b32 v[4:5], v1 offset0:78 offset1:111
	s_waitcnt lgkmcnt(0)
	v_cvt_pk_bf16_f32 v3, v4, v5
	ds_read2_b32 v[4:5], v1 offset0:144 offset1:177
	s_waitcnt lgkmcnt(0)
	v_cvt_pk_bf16_f32 v4, v4, v5
	ds_read2_b32 v[6:7], v1 offset0:210 offset1:243
	s_waitcnt lgkmcnt(0)
	v_cvt_pk_bf16_f32 v5, v6, v7
	ds_read2_b32 v[6:7], v1 offset0:16 offset1:49
	global_store_dwordx4 v[10:11], v[2:5], off
	v_mov_b32_e32 v97, v0
	v_lshl_add_u64 v[10:11], v[8:9], 0, v[96:97]
	s_waitcnt lgkmcnt(0)
	v_cvt_pk_bf16_f32 v2, v6, v7
	ds_read2_b32 v[4:5], v1 offset0:82 offset1:115
	s_waitcnt lgkmcnt(0)
	v_cvt_pk_bf16_f32 v3, v4, v5
	ds_read2_b32 v[4:5], v1 offset0:148 offset1:181
	s_waitcnt lgkmcnt(0)
	v_cvt_pk_bf16_f32 v4, v4, v5
	ds_read2_b32 v[6:7], v1 offset0:214 offset1:247
	s_waitcnt lgkmcnt(0)
	v_cvt_pk_bf16_f32 v5, v6, v7
	ds_read2_b32 v[6:7], v1 offset0:20 offset1:53
	global_store_dwordx4 v[10:11], v[2:5], off
	v_mov_b32_e32 v99, v0
	v_lshl_add_u64 v[10:11], v[8:9], 0, v[98:99]
	s_waitcnt lgkmcnt(0)
	v_cvt_pk_bf16_f32 v2, v6, v7
	ds_read2_b32 v[4:5], v1 offset0:86 offset1:119
	s_waitcnt lgkmcnt(0)
	v_cvt_pk_bf16_f32 v3, v4, v5
	ds_read2_b32 v[4:5], v1 offset0:152 offset1:185
	s_waitcnt lgkmcnt(0)
	v_cvt_pk_bf16_f32 v4, v4, v5
	ds_read2_b32 v[6:7], v1 offset0:218 offset1:251
	s_waitcnt lgkmcnt(0)
	v_cvt_pk_bf16_f32 v5, v6, v7
	ds_read2_b32 v[6:7], v1 offset0:24 offset1:57
	global_store_dwordx4 v[10:11], v[2:5], off
	v_mov_b32_e32 v101, v0
	v_lshl_add_u64 v[10:11], v[8:9], 0, v[100:101]
	s_waitcnt lgkmcnt(0)
	v_cvt_pk_bf16_f32 v2, v6, v7
	ds_read2_b32 v[4:5], v1 offset0:90 offset1:123
	s_waitcnt lgkmcnt(0)
	v_cvt_pk_bf16_f32 v3, v4, v5
	ds_read2_b32 v[4:5], v1 offset0:156 offset1:189
	s_waitcnt lgkmcnt(0)
	v_cvt_pk_bf16_f32 v4, v4, v5
	ds_read2_b32 v[6:7], v1 offset0:222 offset1:255
	s_waitcnt lgkmcnt(0)
	v_cvt_pk_bf16_f32 v5, v6, v7
	ds_read2_b32 v[6:7], v1 offset0:28 offset1:61
	global_store_dwordx4 v[10:11], v[2:5], off
	v_mov_b32_e32 v103, v0
	s_waitcnt lgkmcnt(0)
	v_cvt_pk_bf16_f32 v2, v6, v7
	ds_read2_b32 v[4:5], v1 offset0:94 offset1:127
	s_waitcnt lgkmcnt(0)
	v_cvt_pk_bf16_f32 v3, v4, v5
	ds_read2_b32 v[4:5], v1 offset0:160 offset1:193
	s_waitcnt lgkmcnt(0)
	v_cvt_pk_bf16_f32 v4, v4, v5
	ds_read2_b32 v[6:7], v87 offset0:98 offset1:131
	s_waitcnt lgkmcnt(0)
	v_cvt_pk_bf16_f32 v5, v6, v7
	v_lshl_add_u64 v[6:7], v[8:9], 0, v[102:103]
	global_store_dwordx4 v[6:7], v[2:5], off
	s_waitcnt lgkmcnt(0)

.LBB0_362:
	v_cmp_lt_i32_e32 vcc, s51, v111
	v_add_u32_e32 v144, 0x420, v119
	v_add_u32_e32 v143, 0x428, v119
	v_add_u32_e32 v141, 0x840, v119
	v_add_u32_e32 v139, 0x848, v119
	v_add_u32_e32 v137, 0xc60, v119
	v_add_u32_e32 v135, 0xc68, v119
	v_add_u32_e32 v133, 0x1080, v119
	v_add_u32_e32 v131, 0x1088, v119
	v_add_u32_e32 v129, 0x14a0, v119
	v_add_u32_e32 v127, 0x14a8, v119
	v_add_u32_e32 v125, 0x18c0, v119
	v_add_u32_e32 v123, 0x18c8, v119
	v_add_u32_e32 v121, 0x1ce0, v119
	v_add_u32_e32 v109, 0x1ce8, v119
	v_add_u32_e32 v105, 0x2100, v119
	v_add_u32_e32 v103, 0x2108, v119
	v_add_u32_e32 v101, 0x2520, v119
	v_add_u32_e32 v99, 0x2528, v119
	v_add_u32_e32 v97, 0x2940, v119
	v_add_u32_e32 v95, 0x2948, v119
	v_add_u32_e32 v93, 0x2d60, v119
	v_add_u32_e32 v91, 0x2d68, v119
	v_add_u32_e32 v89, 0x3180, v119
	v_add_u32_e32 v85, 0x3188, v119
	v_add_u32_e32 v83, 0x35a0, v119
	v_add_u32_e32 v81, 0x35a8, v119
	v_add_u32_e32 v79, 0x39c0, v119
	v_add_u32_e32 v77, 0x39c8, v119
	v_add_u32_e32 v75, 0x3de0, v119
	v_add_u32_e32 v73, 0x3de8, v119
	v_lshlrev_b32_e32 v104, 1, v68
	v_add_u32_e32 v87, 0x200, v1
	s_and_saveexec_b64 s[12:13], vcc
	s_xor_b64 s[38:39], exec, s[12:13]
	s_cbranch_execz .LBB0_364
	v_and_b32_e32 v106, 0x7fffff80, v115
	v_add_u32_e32 v2, 0xfffcbe00, v69
	v_and_b32_e32 v107, 0x7e0, v2
	v_or_b32_e32 v62, v106, v113
	v_lshlrev_b32_e32 v2, 2, v107
	v_mov_b32_e32 v3, v0
	v_mov_b32_e32 v63, v0
	v_or_b32_e32 v4, 8, v62
	v_mov_b32_e32 v5, v0
	v_or_b32_e32 v10, 16, v62
	v_mov_b32_e32 v11, v0
	v_or_b32_e32 v12, 24, v62
	v_mov_b32_e32 v13, v0
	v_or_b32_e32 v18, 32, v62
	v_mov_b32_e32 v19, v0
	v_or_b32_e32 v20, 40, v62
	v_mov_b32_e32 v21, v0
	v_or_b32_e32 v26, 48, v62
	v_mov_b32_e32 v27, v0
	v_or_b32_e32 v28, 56, v62
	v_mov_b32_e32 v29, v0
	v_or_b32_e32 v34, 64, v62
	v_mov_b32_e32 v35, v0
	v_or_b32_e32 v36, 0x48, v62
	v_mov_b32_e32 v37, v0
	v_or_b32_e32 v42, 0x50, v62
	v_mov_b32_e32 v43, v0
	v_or_b32_e32 v44, 0x58, v62
	v_mov_b32_e32 v45, v0
	v_or_b32_e32 v50, 0x60, v62
	v_mov_b32_e32 v51, v0
	v_or_b32_e32 v52, 0x68, v62
	v_mov_b32_e32 v53, v0
	v_lshl_add_u64 v[64:65], v[66:67], 0, v[2:3]
	v_lshlrev_b64 v[2:3], 13, v[62:63]
	v_lshlrev_b64 v[4:5], 13, v[4:5]
	v_lshlrev_b64 v[10:11], 13, v[10:11]
	v_lshlrev_b64 v[12:13], 13, v[12:13]
	v_lshlrev_b64 v[18:19], 13, v[18:19]
	v_lshlrev_b64 v[20:21], 13, v[20:21]
	v_lshlrev_b64 v[26:27], 13, v[26:27]
	v_lshlrev_b64 v[28:29], 13, v[28:29]
	v_lshlrev_b64 v[34:35], 13, v[34:35]
	v_lshlrev_b64 v[36:37], 13, v[36:37]
	v_lshlrev_b64 v[42:43], 13, v[42:43]
	v_lshlrev_b64 v[44:45], 13, v[44:45]
	v_lshlrev_b64 v[50:51], 13, v[50:51]
	v_lshlrev_b64 v[52:53], 13, v[52:53]
	v_lshl_add_u64 v[2:3], v[64:65], 0, v[2:3]
	v_lshl_add_u64 v[6:7], v[64:65], 0, v[4:5]
	v_lshl_add_u64 v[10:11], v[64:65], 0, v[10:11]
	v_lshl_add_u64 v[14:15], v[64:65], 0, v[12:13]
	v_lshl_add_u64 v[18:19], v[64:65], 0, v[18:19]
	v_lshl_add_u64 v[22:23], v[64:65], 0, v[20:21]
	v_lshl_add_u64 v[26:27], v[64:65], 0, v[26:27]
	v_lshl_add_u64 v[30:31], v[64:65], 0, v[28:29]
	v_lshl_add_u64 v[34:35], v[64:65], 0, v[34:35]
	v_lshl_add_u64 v[38:39], v[64:65], 0, v[36:37]
	v_lshl_add_u64 v[42:43], v[64:65], 0, v[42:43]
	v_lshl_add_u64 v[46:47], v[64:65], 0, v[44:45]
	v_lshl_add_u64 v[50:51], v[64:65], 0, v[50:51]
	v_lshl_add_u64 v[54:55], v[64:65], 0, v[52:53]
	global_load_dwordx4 v[2:5], v[2:3], off nt
	s_nop 0
	global_load_dwordx4 v[6:9], v[6:7], off nt
	s_nop 0
	global_load_dwordx4 v[10:13], v[10:11], off nt
	s_nop 0
	global_load_dwordx4 v[14:17], v[14:15], off nt
	s_nop 0
	global_load_dwordx4 v[18:21], v[18:19], off nt
	s_nop 0
	global_load_dwordx4 v[22:25], v[22:23], off nt
	s_nop 0
	global_load_dwordx4 v[26:29], v[26:27], off nt
	s_nop 0
	global_load_dwordx4 v[30:33], v[30:31], off nt
	s_nop 0
	global_load_dwordx4 v[34:37], v[34:35], off nt
	s_nop 0
	global_load_dwordx4 v[38:41], v[38:39], off nt
	s_nop 0
	global_load_dwordx4 v[42:45], v[42:43], off nt
	s_nop 0
	global_load_dwordx4 v[46:49], v[46:47], off nt
	s_nop 0
	global_load_dwordx4 v[50:53], v[50:51], off nt
	s_nop 0
	global_load_dwordx4 v[54:57], v[54:55], off nt
	v_or_b32_e32 v58, 0x70, v62
	v_mov_b32_e32 v59, v0
	v_lshlrev_b64 v[58:59], 13, v[58:59]
	v_lshl_add_u64 v[58:59], v[64:65], 0, v[58:59]
	v_or_b32_e32 v62, 0x78, v62
	global_load_dwordx4 v[58:61], v[58:59], off nt
	v_lshlrev_b64 v[62:63], 13, v[62:63]
	v_lshl_add_u64 v[62:63], v[64:65], 0, v[62:63]
	global_load_dwordx4 v[62:65], v[62:63], off nt
	s_waitcnt vmcnt(0)
	ds_write2_b32 v119, v2, v3 offset1:1
	ds_write2_b32 v119, v4, v5 offset0:2 offset1:3
	ds_write2_b32 v144, v6, v7 offset1:1
	ds_write2_b32 v143, v8, v9 offset1:1
	ds_write2_b32 v141, v10, v11 offset1:1
	ds_write2_b32 v139, v12, v13 offset1:1
	ds_write2_b32 v137, v14, v15 offset1:1
	ds_write2_b32 v135, v16, v17 offset1:1
	ds_write2_b32 v133, v18, v19 offset1:1
	ds_write2_b32 v131, v20, v21 offset1:1
	ds_write2_b32 v129, v22, v23 offset1:1
	ds_write2_b32 v127, v24, v25 offset1:1
	ds_write2_b32 v125, v26, v27 offset1:1
	ds_write2_b32 v123, v28, v29 offset1:1
	ds_write2_b32 v121, v30, v31 offset1:1
	ds_write2_b32 v109, v32, v33 offset1:1
	ds_write2_b32 v105, v34, v35 offset1:1
	ds_write2_b32 v103, v36, v37 offset1:1
	ds_write2_b32 v101, v38, v39 offset1:1
	ds_write2_b32 v99, v40, v41 offset1:1
	ds_write2_b32 v97, v42, v43 offset1:1
	ds_write2_b32 v95, v44, v45 offset1:1
	ds_write2_b32 v93, v46, v47 offset1:1
	ds_write2_b32 v91, v48, v49 offset1:1
	ds_write2_b32 v89, v50, v51 offset1:1
	ds_write2_b32 v85, v52, v53 offset1:1
	ds_write2_b32 v83, v54, v55 offset1:1
	ds_write2_b32 v81, v56, v57 offset1:1
	ds_write2_b32 v79, v58, v59 offset1:1
	ds_write2_b32 v77, v60, v61 offset1:1
	ds_write2_b32 v75, v62, v63 offset1:1
	ds_write2_b32 v73, v64, v65 offset1:1
	s_waitcnt lgkmcnt(0)
	v_lshlrev_b32_e32 v6, 13, v107
	v_mov_b32_e32 v7, v0
	ds_read2_b32 v[2:3], v1 offset1:33
	v_lshl_add_u64 v[6:7], s[20:21], 0, v[6:7]
	v_lshlrev_b32_e32 v10, 1, v106
	v_mov_b32_e32 v11, v0
	s_waitcnt lgkmcnt(0)
	v_cvt_pk_bf16_f32 v2, v2, v3
	ds_read2_b32 v[4:5], v1 offset0:66 offset1:99
	v_lshl_add_u64 v[6:7], v[6:7], 0, v[10:11]
	v_mov_b32_e32 v105, v0
	s_waitcnt lgkmcnt(0)
	v_cvt_pk_bf16_f32 v3, v4, v5
	ds_read2_b32 v[4:5], v1 offset0:132 offset1:165
	v_lshl_add_u64 v[6:7], v[6:7], 0, v[104:105]
	v_mov_b32_e32 v73, v0
	s_waitcnt lgkmcnt(0)
	v_cvt_pk_bf16_f32 v4, v4, v5
	ds_read2_b32 v[8:9], v1 offset0:198 offset1:231
	s_waitcnt lgkmcnt(0)
	v_cvt_pk_bf16_f32 v5, v8, v9
	v_lshl_add_u64 v[10:11], v[6:7], 0, v[72:73]
	ds_read2_b32 v[8:9], v1 offset0:4 offset1:37
	global_store_dwordx4 v[10:11], v[2:5], off
	v_mov_b32_e32 v75, v0
	v_lshl_add_u64 v[10:11], v[6:7], 0, v[74:75]
	s_waitcnt lgkmcnt(0)
	v_cvt_pk_bf16_f32 v2, v8, v9
	ds_read2_b32 v[4:5], v1 offset0:70 offset1:103
	s_waitcnt lgkmcnt(0)
	v_cvt_pk_bf16_f32 v3, v4, v5
	ds_read2_b32 v[4:5], v1 offset0:136 offset1:169
	s_waitcnt lgkmcnt(0)
	v_cvt_pk_bf16_f32 v4, v4, v5
	ds_read2_b32 v[8:9], v1 offset0:202 offset1:235
	s_waitcnt lgkmcnt(0)
	v_cvt_pk_bf16_f32 v5, v8, v9
	ds_read2_b32 v[8:9], v1 offset0:8 offset1:41
	global_store_dwordx4 v[10:11], v[2:5], off
	v_mov_b32_e32 v77, v0
	v_lshl_add_u64 v[10:11], v[6:7], 0, v[76:77]
	s_waitcnt lgkmcnt(0)
	v_cvt_pk_bf16_f32 v2, v8, v9
	ds_read2_b32 v[4:5], v1 offset0:74 offset1:107
	s_waitcnt lgkmcnt(0)
	v_cvt_pk_bf16_f32 v3, v4, v5
	ds_read2_b32 v[4:5], v1 offset0:140 offset1:173
	s_waitcnt lgkmcnt(0)
	v_cvt_pk_bf16_f32 v4, v4, v5
	ds_read2_b32 v[8:9], v1 offset0:206 offset1:239
	s_waitcnt lgkmcnt(0)
	v_cvt_pk_bf16_f32 v5, v8, v9
	ds_read2_b32 v[8:9], v1 offset0:12 offset1:45
	global_store_dwordx4 v[10:11], v[2:5], off
	v_mov_b32_e32 v79, v0
	v_lshl_add_u64 v[10:11], v[6:7], 0, v[78:79]
	s_waitcnt lgkmcnt(0)
	v_cvt_pk_bf16_f32 v2, v8, v9
	ds_read2_b32 v[4:5], v1 offset0:78 offset1:111
	s_waitcnt lgkmcnt(0)
	v_cvt_pk_bf16_f32 v3, v4, v5
	ds_read2_b32 v[4:5], v1 offset0:144 offset1:177
	s_waitcnt lgkmcnt(0)
	v_cvt_pk_bf16_f32 v4, v4, v5
	ds_read2_b32 v[8:9], v1 offset0:210 offset1:243
	s_waitcnt lgkmcnt(0)
	v_cvt_pk_bf16_f32 v5, v8, v9
	ds_read2_b32 v[8:9], v1 offset0:16 offset1:49
	global_store_dwordx4 v[10:11], v[2:5], off
	v_mov_b32_e32 v81, v0
	v_lshl_add_u64 v[10:11], v[6:7], 0, v[80:81]
	s_waitcnt lgkmcnt(0)
	v_cvt_pk_bf16_f32 v2, v8, v9
	ds_read2_b32 v[4:5], v1 offset0:82 offset1:115
	s_waitcnt lgkmcnt(0)
	v_cvt_pk_bf16_f32 v3, v4, v5
	ds_read2_b32 v[4:5], v1 offset0:148 offset1:181
	s_waitcnt lgkmcnt(0)
	v_cvt_pk_bf16_f32 v4, v4, v5
	ds_read2_b32 v[8:9], v1 offset0:214 offset1:247
	s_waitcnt lgkmcnt(0)
	v_cvt_pk_bf16_f32 v5, v8, v9
	ds_read2_b32 v[8:9], v1 offset0:20 offset1:53
	global_store_dwordx4 v[10:11], v[2:5], off
	v_mov_b32_e32 v83, v0
	v_lshl_add_u64 v[10:11], v[6:7], 0, v[82:83]
	s_waitcnt lgkmcnt(0)
	v_cvt_pk_bf16_f32 v2, v8, v9
	ds_read2_b32 v[4:5], v1 offset0:86 offset1:119
	s_waitcnt lgkmcnt(0)
	v_cvt_pk_bf16_f32 v3, v4, v5
	ds_read2_b32 v[4:5], v1 offset0:152 offset1:185
	s_waitcnt lgkmcnt(0)
	v_cvt_pk_bf16_f32 v4, v4, v5
	ds_read2_b32 v[8:9], v1 offset0:218 offset1:251
	s_waitcnt lgkmcnt(0)
	v_cvt_pk_bf16_f32 v5, v8, v9
	ds_read2_b32 v[8:9], v1 offset0:24 offset1:57
	global_store_dwordx4 v[10:11], v[2:5], off
	v_mov_b32_e32 v85, v0
	v_lshl_add_u64 v[10:11], v[6:7], 0, v[84:85]
	s_waitcnt lgkmcnt(0)
	v_cvt_pk_bf16_f32 v2, v8, v9
	ds_read2_b32 v[4:5], v1 offset0:90 offset1:123
	s_waitcnt lgkmcnt(0)
	v_cvt_pk_bf16_f32 v3, v4, v5
	ds_read2_b32 v[4:5], v1 offset0:156 offset1:189
	s_waitcnt lgkmcnt(0)
	v_cvt_pk_bf16_f32 v4, v4, v5
	ds_read2_b32 v[8:9], v1 offset0:222 offset1:255
	s_waitcnt lgkmcnt(0)
	v_cvt_pk_bf16_f32 v5, v8, v9
	ds_read2_b32 v[8:9], v1 offset0:28 offset1:61
	global_store_dwordx4 v[10:11], v[2:5], off
	s_waitcnt lgkmcnt(0)
	s_nop 0
	v_cvt_pk_bf16_f32 v2, v8, v9
	ds_read2_b32 v[4:5], v1 offset0:94 offset1:127
	s_waitcnt lgkmcnt(0)
	v_cvt_pk_bf16_f32 v3, v4, v5
	ds_read2_b32 v[4:5], v1 offset0:160 offset1:193
	s_waitcnt lgkmcnt(0)
	v_cvt_pk_bf16_f32 v4, v4, v5
	ds_read2_b32 v[8:9], v87 offset0:98 offset1:131
	v_mov_b32_e32 v87, v0
	v_lshl_add_u64 v[6:7], v[6:7], 0, v[86:87]
	s_waitcnt lgkmcnt(0)
	v_cvt_pk_bf16_f32 v5, v8, v9
	global_store_dwordx4 v[6:7], v[2:5], off
	s_waitcnt lgkmcnt(0)

.LBB0_413:
	s_waitcnt vmcnt(0)
	v_pk_mul_f32 v[2:3], v[2:3], v[114:115] op_sel_hi:[1,0]
	ds_write2_b32 v117, v2, v3 offset1:1
	v_pk_mul_f32 v[2:3], v[4:5], v[114:115] op_sel_hi:[1,0]
	ds_write2_b32 v117, v2, v3 offset0:2 offset1:3
	v_pk_mul_f32 v[2:3], v[6:7], v[112:113] op_sel_hi:[1,0]
	ds_write2_b32 v146, v2, v3 offset1:1
	v_pk_mul_f32 v[2:3], v[8:9], v[112:113] op_sel_hi:[1,0]
	ds_write2_b32 v145, v2, v3 offset1:1
	v_pk_mul_f32 v[2:3], v[10:11], v[120:121] op_sel_hi:[1,0]
	ds_write2_b32 v143, v2, v3 offset1:1
	v_pk_mul_f32 v[2:3], v[12:13], v[120:121] op_sel_hi:[1,0]
	ds_write2_b32 v141, v2, v3 offset1:1
	v_pk_mul_f32 v[2:3], v[14:15], v[116:117] op_sel_hi:[1,0]
	ds_write2_b32 v139, v2, v3 offset1:1
	v_pk_mul_f32 v[2:3], v[16:17], v[116:117] op_sel_hi:[1,0]
	ds_write2_b32 v137, v2, v3 offset1:1
	v_pk_mul_f32 v[2:3], v[18:19], v[124:125] op_sel_hi:[1,0]
	ds_write2_b32 v135, v2, v3 offset1:1
	v_pk_mul_f32 v[2:3], v[20:21], v[124:125] op_sel_hi:[1,0]
	ds_write2_b32 v133, v2, v3 offset1:1
	v_pk_mul_f32 v[2:3], v[22:23], v[122:123] op_sel_hi:[1,0]
	ds_write2_b32 v131, v2, v3 offset1:1
	v_pk_mul_f32 v[2:3], v[24:25], v[122:123] op_sel_hi:[1,0]
	ds_write2_b32 v129, v2, v3 offset1:1
	v_pk_mul_f32 v[2:3], v[26:27], v[128:129] op_sel_hi:[1,0]
	ds_write2_b32 v127, v2, v3 offset1:1
	v_pk_mul_f32 v[2:3], v[28:29], v[128:129] op_sel_hi:[1,0]
	ds_write2_b32 v125, v2, v3 offset1:1
	v_pk_mul_f32 v[2:3], v[30:31], v[126:127] op_sel_hi:[1,0]
	ds_write2_b32 v123, v2, v3 offset1:1
	v_pk_mul_f32 v[2:3], v[32:33], v[126:127] op_sel_hi:[1,0]
	ds_write2_b32 v111, v2, v3 offset1:1
	v_pk_mul_f32 v[2:3], v[34:35], v[132:133] op_sel_hi:[1,0]
	ds_write2_b32 v107, v2, v3 offset1:1
	v_pk_mul_f32 v[2:3], v[36:37], v[132:133] op_sel_hi:[1,0]
	ds_write2_b32 v105, v2, v3 offset1:1
	v_pk_mul_f32 v[2:3], v[38:39], v[130:131] op_sel_hi:[1,0]
	ds_write2_b32 v103, v2, v3 offset1:1
	v_pk_mul_f32 v[2:3], v[40:41], v[130:131] op_sel_hi:[1,0]
	ds_write2_b32 v101, v2, v3 offset1:1
	v_pk_mul_f32 v[2:3], v[42:43], v[136:137] op_sel_hi:[1,0]
	ds_write2_b32 v99, v2, v3 offset1:1
	v_pk_mul_f32 v[2:3], v[44:45], v[136:137] op_sel_hi:[1,0]
	ds_write2_b32 v97, v2, v3 offset1:1
	v_pk_mul_f32 v[2:3], v[46:47], v[134:135] op_sel_hi:[1,0]
	ds_write2_b32 v95, v2, v3 offset1:1
	v_pk_mul_f32 v[2:3], v[48:49], v[134:135] op_sel_hi:[1,0]
	ds_write2_b32 v93, v2, v3 offset1:1
	v_pk_mul_f32 v[2:3], v[50:51], v[140:141] op_sel_hi:[1,0]
	ds_write2_b32 v91, v2, v3 offset1:1
	v_pk_mul_f32 v[2:3], v[52:53], v[140:141] op_sel_hi:[1,0]
	ds_write2_b32 v87, v2, v3 offset1:1
	v_pk_mul_f32 v[2:3], v[54:55], v[138:139] op_sel_hi:[1,0]
	ds_write2_b32 v85, v2, v3 offset1:1
	v_pk_mul_f32 v[2:3], v[56:57], v[138:139] op_sel_hi:[1,0]
	ds_write2_b32 v83, v2, v3 offset1:1
	v_pk_mul_f32 v[2:3], v[58:59], v[144:145] op_sel_hi:[1,0]
	ds_write2_b32 v81, v2, v3 offset1:1
	v_pk_mul_f32 v[2:3], v[60:61], v[144:145] op_sel_hi:[1,0]
	ds_write2_b32 v79, v2, v3 offset1:1
	v_pk_mul_f32 v[2:3], v[62:63], v[142:143] op_sel_hi:[1,0]
	ds_write2_b32 v77, v2, v3 offset1:1
	v_pk_mul_f32 v[2:3], v[64:65], v[142:143] op_sel_hi:[1,0]
	ds_write2_b32 v75, v2, v3 offset1:1
	s_waitcnt lgkmcnt(0)
	ds_read2_b32 v[2:3], v69 offset1:33
	v_ashrrev_i32_e32 v111, 31, v110
	s_waitcnt lgkmcnt(0)
	v_cvt_pk_bf16_f32 v2, v2, v3
	ds_read2_b32 v[4:5], v69 offset0:66 offset1:99
	v_lshl_add_u64 v[8:9], v[110:111], 1, v[108:109]
	v_mov_b32_e32 v107, v0
	s_waitcnt lgkmcnt(0)
	v_cvt_pk_bf16_f32 v3, v4, v5
	ds_read2_b32 v[4:5], v69 offset0:132 offset1:165
	v_lshl_add_u64 v[8:9], v[8:9], 0, v[106:107]
	v_mov_b32_e32 v91, v0
	s_waitcnt lgkmcnt(0)
	v_cvt_pk_bf16_f32 v4, v4, v5
	ds_read2_b32 v[6:7], v69 offset0:198 offset1:231
	s_waitcnt lgkmcnt(0)
	v_cvt_pk_bf16_f32 v5, v6, v7
	v_lshl_add_u64 v[10:11], v[8:9], 0, v[90:91]
	ds_read2_b32 v[6:7], v69 offset0:4 offset1:37
	global_store_dwordx4 v[10:11], v[2:5], off
	v_mov_b32_e32 v93, v0
	v_lshl_add_u64 v[10:11], v[8:9], 0, v[92:93]
	s_waitcnt lgkmcnt(0)
	v_cvt_pk_bf16_f32 v2, v6, v7
	ds_read2_b32 v[4:5], v69 offset0:70 offset1:103
	s_waitcnt lgkmcnt(0)
	v_cvt_pk_bf16_f32 v3, v4, v5
	ds_read2_b32 v[4:5], v69 offset0:136 offset1:169
	s_waitcnt lgkmcnt(0)
	v_cvt_pk_bf16_f32 v4, v4, v5
	ds_read2_b32 v[6:7], v69 offset0:202 offset1:235
	s_waitcnt lgkmcnt(0)
	v_cvt_pk_bf16_f32 v5, v6, v7
	ds_read2_b32 v[6:7], v69 offset0:8 offset1:41
	global_store_dwordx4 v[10:11], v[2:5], off
	v_mov_b32_e32 v95, v0
	v_lshl_add_u64 v[10:11], v[8:9], 0, v[94:95]
	s_waitcnt lgkmcnt(0)
	v_cvt_pk_bf16_f32 v2, v6, v7
	ds_read2_b32 v[4:5], v69 offset0:74 offset1:107
	s_waitcnt lgkmcnt(0)
	v_cvt_pk_bf16_f32 v3, v4, v5
	ds_read2_b32 v[4:5], v69 offset0:140 offset1:173
	s_waitcnt lgkmcnt(0)
	v_cvt_pk_bf16_f32 v4, v4, v5
	ds_read2_b32 v[6:7], v69 offset0:206 offset1:239
	s_waitcnt lgkmcnt(0)
	v_cvt_pk_bf16_f32 v5, v6, v7
	ds_read2_b32 v[6:7], v69 offset0:12 offset1:45
	global_store_dwordx4 v[10:11], v[2:5], off
	v_mov_b32_e32 v97, v0
	v_lshl_add_u64 v[10:11], v[8:9], 0, v[96:97]
	s_waitcnt lgkmcnt(0)
	v_cvt_pk_bf16_f32 v2, v6, v7
	ds_read2_b32 v[4:5], v69 offset0:78 offset1:111
	s_waitcnt lgkmcnt(0)
	v_cvt_pk_bf16_f32 v3, v4, v5
	ds_read2_b32 v[4:5], v69 offset0:144 offset1:177
	s_waitcnt lgkmcnt(0)
	v_cvt_pk_bf16_f32 v4, v4, v5
	ds_read2_b32 v[6:7], v69 offset0:210 offset1:243
	s_waitcnt lgkmcnt(0)
	v_cvt_pk_bf16_f32 v5, v6, v7
	ds_read2_b32 v[6:7], v69 offset0:16 offset1:49
	global_store_dwordx4 v[10:11], v[2:5], off
	v_mov_b32_e32 v99, v0
	v_lshl_add_u64 v[10:11], v[8:9], 0, v[98:99]
	s_waitcnt lgkmcnt(0)
	v_cvt_pk_bf16_f32 v2, v6, v7
	ds_read2_b32 v[4:5], v69 offset0:82 offset1:115
	s_waitcnt lgkmcnt(0)
	v_cvt_pk_bf16_f32 v3, v4, v5
	ds_read2_b32 v[4:5], v69 offset0:148 offset1:181
	s_waitcnt lgkmcnt(0)
	v_cvt_pk_bf16_f32 v4, v4, v5
	ds_read2_b32 v[6:7], v69 offset0:214 offset1:247
	s_waitcnt lgkmcnt(0)
	v_cvt_pk_bf16_f32 v5, v6, v7
	ds_read2_b32 v[6:7], v69 offset0:20 offset1:53
	global_store_dwordx4 v[10:11], v[2:5], off
	v_mov_b32_e32 v101, v0
	v_lshl_add_u64 v[10:11], v[8:9], 0, v[100:101]
	s_waitcnt lgkmcnt(0)
	v_cvt_pk_bf16_f32 v2, v6, v7
	ds_read2_b32 v[4:5], v69 offset0:86 offset1:119
	s_waitcnt lgkmcnt(0)
	v_cvt_pk_bf16_f32 v3, v4, v5
	ds_read2_b32 v[4:5], v69 offset0:152 offset1:185
	s_waitcnt lgkmcnt(0)
	v_cvt_pk_bf16_f32 v4, v4, v5
	ds_read2_b32 v[6:7], v69 offset0:218 offset1:251
	s_waitcnt lgkmcnt(0)
	v_cvt_pk_bf16_f32 v5, v6, v7
	ds_read2_b32 v[6:7], v69 offset0:24 offset1:57
	global_store_dwordx4 v[10:11], v[2:5], off
	v_mov_b32_e32 v103, v0
	v_lshl_add_u64 v[10:11], v[8:9], 0, v[102:103]
	s_waitcnt lgkmcnt(0)
	v_cvt_pk_bf16_f32 v2, v6, v7
	ds_read2_b32 v[4:5], v69 offset0:90 offset1:123
	s_waitcnt lgkmcnt(0)
	v_cvt_pk_bf16_f32 v3, v4, v5
	ds_read2_b32 v[4:5], v69 offset0:156 offset1:189
	s_waitcnt lgkmcnt(0)
	v_cvt_pk_bf16_f32 v4, v4, v5
	ds_read2_b32 v[6:7], v69 offset0:222 offset1:255
	s_waitcnt lgkmcnt(0)
	v_cvt_pk_bf16_f32 v5, v6, v7
	ds_read2_b32 v[6:7], v69 offset0:28 offset1:61
	global_store_dwordx4 v[10:11], v[2:5], off
	v_mov_b32_e32 v105, v0
	s_waitcnt lgkmcnt(0)
	v_cvt_pk_bf16_f32 v2, v6, v7
	ds_read2_b32 v[4:5], v69 offset0:94 offset1:127
	s_waitcnt lgkmcnt(0)
	v_cvt_pk_bf16_f32 v3, v4, v5
	ds_read2_b32 v[4:5], v69 offset0:160 offset1:193
	s_waitcnt lgkmcnt(0)
	v_cvt_pk_bf16_f32 v4, v4, v5
	ds_read2_b32 v[6:7], v89 offset0:98 offset1:131
	s_waitcnt lgkmcnt(0)
	v_cvt_pk_bf16_f32 v5, v6, v7
	v_lshl_add_u64 v[6:7], v[8:9], 0, v[104:105]
	global_store_dwordx4 v[6:7], v[2:5], off
	s_waitcnt lgkmcnt(0)

.LBB0_415:
	v_cmp_lt_i32_e32 vcc, s51, v121
	v_add_u32_e32 v146, 0x420, v117
	v_add_u32_e32 v145, 0x428, v117
	v_add_u32_e32 v143, 0x840, v117
	v_add_u32_e32 v141, 0x848, v117
	v_add_u32_e32 v139, 0xc60, v117
	v_add_u32_e32 v137, 0xc68, v117
	v_add_u32_e32 v135, 0x1080, v117
	v_add_u32_e32 v133, 0x1088, v117
	v_add_u32_e32 v131, 0x14a0, v117
	v_add_u32_e32 v129, 0x14a8, v117
	v_add_u32_e32 v127, 0x18c0, v117
	v_add_u32_e32 v125, 0x18c8, v117
	v_add_u32_e32 v123, 0x1ce0, v117
	v_add_u32_e32 v111, 0x1ce8, v117
	v_add_u32_e32 v107, 0x2100, v117
	v_add_u32_e32 v105, 0x2108, v117
	v_add_u32_e32 v103, 0x2520, v117
	v_add_u32_e32 v101, 0x2528, v117
	v_add_u32_e32 v99, 0x2940, v117
	v_add_u32_e32 v97, 0x2948, v117
	v_add_u32_e32 v95, 0x2d60, v117
	v_add_u32_e32 v93, 0x2d68, v117
	v_add_u32_e32 v91, 0x3180, v117
	v_add_u32_e32 v87, 0x3188, v117
	v_add_u32_e32 v85, 0x35a0, v117
	v_add_u32_e32 v83, 0x35a8, v117
	v_add_u32_e32 v81, 0x39c0, v117
	v_add_u32_e32 v79, 0x39c8, v117
	v_add_u32_e32 v77, 0x3de0, v117
	v_add_u32_e32 v75, 0x3de8, v117
	v_lshlrev_b32_e32 v106, 1, v68
	v_add_u32_e32 v89, 0x200, v69
	s_and_saveexec_b64 s[12:13], vcc
	s_xor_b64 s[20:21], exec, s[12:13]
	s_cbranch_execz .LBB0_417
	v_and_b32_e32 v108, 0x7fffff80, v115
	v_add_u32_e32 v2, 0xfffcbe00, v113
	v_and_b32_e32 v109, 0x7e0, v2
	v_or_b32_e32 v62, v108, v67
	v_lshlrev_b32_e32 v2, 2, v109
	v_mov_b32_e32 v3, v0
	v_mov_b32_e32 v63, v0
	v_or_b32_e32 v4, 8, v62
	v_mov_b32_e32 v5, v0
	v_or_b32_e32 v10, 16, v62
	v_mov_b32_e32 v11, v0
	v_or_b32_e32 v12, 24, v62
	v_mov_b32_e32 v13, v0
	v_or_b32_e32 v18, 32, v62
	v_mov_b32_e32 v19, v0
	v_or_b32_e32 v20, 40, v62
	v_mov_b32_e32 v21, v0
	v_or_b32_e32 v26, 48, v62
	v_mov_b32_e32 v27, v0
	v_or_b32_e32 v28, 56, v62
	v_mov_b32_e32 v29, v0
	v_or_b32_e32 v34, 64, v62
	v_mov_b32_e32 v35, v0
	v_or_b32_e32 v36, 0x48, v62
	v_mov_b32_e32 v37, v0
	v_or_b32_e32 v42, 0x50, v62
	v_mov_b32_e32 v43, v0
	v_or_b32_e32 v44, 0x58, v62
	v_mov_b32_e32 v45, v0
	v_or_b32_e32 v50, 0x60, v62
	v_mov_b32_e32 v51, v0
	v_or_b32_e32 v52, 0x68, v62
	v_mov_b32_e32 v53, v0
	v_lshl_add_u64 v[64:65], v[70:71], 0, v[2:3]
	v_lshlrev_b64 v[2:3], 13, v[62:63]
	v_lshlrev_b64 v[4:5], 13, v[4:5]
	v_lshlrev_b64 v[10:11], 13, v[10:11]
	v_lshlrev_b64 v[12:13], 13, v[12:13]
	v_lshlrev_b64 v[18:19], 13, v[18:19]
	v_lshlrev_b64 v[20:21], 13, v[20:21]
	v_lshlrev_b64 v[26:27], 13, v[26:27]
	v_lshlrev_b64 v[28:29], 13, v[28:29]
	v_lshlrev_b64 v[34:35], 13, v[34:35]
	v_lshlrev_b64 v[36:37], 13, v[36:37]
	v_lshlrev_b64 v[42:43], 13, v[42:43]
	v_lshlrev_b64 v[44:45], 13, v[44:45]
	v_lshlrev_b64 v[50:51], 13, v[50:51]
	v_lshlrev_b64 v[52:53], 13, v[52:53]
	v_lshl_add_u64 v[2:3], v[64:65], 0, v[2:3]
	v_lshl_add_u64 v[6:7], v[64:65], 0, v[4:5]
	v_lshl_add_u64 v[10:11], v[64:65], 0, v[10:11]
	v_lshl_add_u64 v[14:15], v[64:65], 0, v[12:13]
	v_lshl_add_u64 v[18:19], v[64:65], 0, v[18:19]
	v_lshl_add_u64 v[22:23], v[64:65], 0, v[20:21]
	v_lshl_add_u64 v[26:27], v[64:65], 0, v[26:27]
	v_lshl_add_u64 v[30:31], v[64:65], 0, v[28:29]
	v_lshl_add_u64 v[34:35], v[64:65], 0, v[34:35]
	v_lshl_add_u64 v[38:39], v[64:65], 0, v[36:37]
	v_lshl_add_u64 v[42:43], v[64:65], 0, v[42:43]
	v_lshl_add_u64 v[46:47], v[64:65], 0, v[44:45]
	v_lshl_add_u64 v[50:51], v[64:65], 0, v[50:51]
	v_lshl_add_u64 v[54:55], v[64:65], 0, v[52:53]
	global_load_dwordx4 v[2:5], v[2:3], off nt
	s_nop 0
	global_load_dwordx4 v[6:9], v[6:7], off nt
	s_nop 0
	global_load_dwordx4 v[10:13], v[10:11], off nt
	s_nop 0
	global_load_dwordx4 v[14:17], v[14:15], off nt
	s_nop 0
	global_load_dwordx4 v[18:21], v[18:19], off nt
	s_nop 0
	global_load_dwordx4 v[22:25], v[22:23], off nt
	s_nop 0
	global_load_dwordx4 v[26:29], v[26:27], off nt
	s_nop 0
	global_load_dwordx4 v[30:33], v[30:31], off nt
	s_nop 0
	global_load_dwordx4 v[34:37], v[34:35], off nt
	s_nop 0
	global_load_dwordx4 v[38:41], v[38:39], off nt
	s_nop 0
	global_load_dwordx4 v[42:45], v[42:43], off nt
	s_nop 0
	global_load_dwordx4 v[46:49], v[46:47], off nt
	s_nop 0
	global_load_dwordx4 v[50:53], v[50:51], off nt
	s_nop 0
	global_load_dwordx4 v[54:57], v[54:55], off nt
	v_or_b32_e32 v58, 0x70, v62
	v_mov_b32_e32 v59, v0
	v_lshlrev_b64 v[58:59], 13, v[58:59]
	v_lshl_add_u64 v[58:59], v[64:65], 0, v[58:59]
	v_or_b32_e32 v62, 0x78, v62
	global_load_dwordx4 v[58:61], v[58:59], off nt
	v_lshlrev_b64 v[62:63], 13, v[62:63]
	v_lshl_add_u64 v[62:63], v[64:65], 0, v[62:63]
	global_load_dwordx4 v[62:65], v[62:63], off nt
	s_waitcnt vmcnt(0)
	ds_write2_b32 v117, v2, v3 offset1:1
	ds_write2_b32 v117, v4, v5 offset0:2 offset1:3
	ds_write2_b32 v146, v6, v7 offset1:1
	ds_write2_b32 v145, v8, v9 offset1:1
	ds_write2_b32 v143, v10, v11 offset1:1
	ds_write2_b32 v141, v12, v13 offset1:1
	ds_write2_b32 v139, v14, v15 offset1:1
	ds_write2_b32 v137, v16, v17 offset1:1
	ds_write2_b32 v135, v18, v19 offset1:1
	ds_write2_b32 v133, v20, v21 offset1:1
	ds_write2_b32 v131, v22, v23 offset1:1
	ds_write2_b32 v129, v24, v25 offset1:1
	ds_write2_b32 v127, v26, v27 offset1:1
	ds_write2_b32 v125, v28, v29 offset1:1
	ds_write2_b32 v123, v30, v31 offset1:1
	ds_write2_b32 v111, v32, v33 offset1:1
	ds_write2_b32 v107, v34, v35 offset1:1
	ds_write2_b32 v105, v36, v37 offset1:1
	ds_write2_b32 v103, v38, v39 offset1:1
	ds_write2_b32 v101, v40, v41 offset1:1
	ds_write2_b32 v99, v42, v43 offset1:1
	ds_write2_b32 v97, v44, v45 offset1:1
	ds_write2_b32 v95, v46, v47 offset1:1
	ds_write2_b32 v93, v48, v49 offset1:1
	ds_write2_b32 v91, v50, v51 offset1:1
	ds_write2_b32 v87, v52, v53 offset1:1
	ds_write2_b32 v85, v54, v55 offset1:1
	ds_write2_b32 v83, v56, v57 offset1:1
	ds_write2_b32 v81, v58, v59 offset1:1
	ds_write2_b32 v79, v60, v61 offset1:1
	ds_write2_b32 v77, v62, v63 offset1:1
	ds_write2_b32 v75, v64, v65 offset1:1
	s_waitcnt lgkmcnt(0)
	v_lshlrev_b32_e32 v6, 13, v109
	v_mov_b32_e32 v7, v0
	ds_read2_b32 v[2:3], v69 offset1:33
	v_lshl_add_u64 v[6:7], s[6:7], 0, v[6:7]
	v_lshlrev_b32_e32 v10, 1, v108
	v_mov_b32_e32 v11, v0
	s_waitcnt lgkmcnt(0)
	v_cvt_pk_bf16_f32 v2, v2, v3
	ds_read2_b32 v[4:5], v69 offset0:66 offset1:99
	v_lshl_add_u64 v[6:7], v[6:7], 0, v[10:11]
	v_mov_b32_e32 v107, v0
	s_waitcnt lgkmcnt(0)
	v_cvt_pk_bf16_f32 v3, v4, v5
	ds_read2_b32 v[4:5], v69 offset0:132 offset1:165
	v_lshl_add_u64 v[6:7], v[6:7], 0, v[106:107]
	v_mov_b32_e32 v75, v0
	s_waitcnt lgkmcnt(0)
	v_cvt_pk_bf16_f32 v4, v4, v5
	ds_read2_b32 v[8:9], v69 offset0:198 offset1:231
	s_waitcnt lgkmcnt(0)
	v_cvt_pk_bf16_f32 v5, v8, v9
	v_lshl_add_u64 v[10:11], v[6:7], 0, v[74:75]
	ds_read2_b32 v[8:9], v69 offset0:4 offset1:37
	global_store_dwordx4 v[10:11], v[2:5], off
	v_mov_b32_e32 v77, v0
	v_lshl_add_u64 v[10:11], v[6:7], 0, v[76:77]
	s_waitcnt lgkmcnt(0)
	v_cvt_pk_bf16_f32 v2, v8, v9
	ds_read2_b32 v[4:5], v69 offset0:70 offset1:103
	s_waitcnt lgkmcnt(0)
	v_cvt_pk_bf16_f32 v3, v4, v5
	ds_read2_b32 v[4:5], v69 offset0:136 offset1:169
	s_waitcnt lgkmcnt(0)
	v_cvt_pk_bf16_f32 v4, v4, v5
	ds_read2_b32 v[8:9], v69 offset0:202 offset1:235
	s_waitcnt lgkmcnt(0)
	v_cvt_pk_bf16_f32 v5, v8, v9
	ds_read2_b32 v[8:9], v69 offset0:8 offset1:41
	global_store_dwordx4 v[10:11], v[2:5], off
	v_mov_b32_e32 v79, v0
	v_lshl_add_u64 v[10:11], v[6:7], 0, v[78:79]
	s_waitcnt lgkmcnt(0)
	v_cvt_pk_bf16_f32 v2, v8, v9
	ds_read2_b32 v[4:5], v69 offset0:74 offset1:107
	s_waitcnt lgkmcnt(0)
	v_cvt_pk_bf16_f32 v3, v4, v5
	ds_read2_b32 v[4:5], v69 offset0:140 offset1:173
	s_waitcnt lgkmcnt(0)
	v_cvt_pk_bf16_f32 v4, v4, v5
	ds_read2_b32 v[8:9], v69 offset0:206 offset1:239
	s_waitcnt lgkmcnt(0)
	v_cvt_pk_bf16_f32 v5, v8, v9
	ds_read2_b32 v[8:9], v69 offset0:12 offset1:45
	global_store_dwordx4 v[10:11], v[2:5], off
	v_mov_b32_e32 v81, v0
	v_lshl_add_u64 v[10:11], v[6:7], 0, v[80:81]
	s_waitcnt lgkmcnt(0)
	v_cvt_pk_bf16_f32 v2, v8, v9
	ds_read2_b32 v[4:5], v69 offset0:78 offset1:111
	s_waitcnt lgkmcnt(0)
	v_cvt_pk_bf16_f32 v3, v4, v5
	ds_read2_b32 v[4:5], v69 offset0:144 offset1:177
	s_waitcnt lgkmcnt(0)
	v_cvt_pk_bf16_f32 v4, v4, v5
	ds_read2_b32 v[8:9], v69 offset0:210 offset1:243
	s_waitcnt lgkmcnt(0)
	v_cvt_pk_bf16_f32 v5, v8, v9
	ds_read2_b32 v[8:9], v69 offset0:16 offset1:49
	global_store_dwordx4 v[10:11], v[2:5], off
	v_mov_b32_e32 v83, v0
	v_lshl_add_u64 v[10:11], v[6:7], 0, v[82:83]
	s_waitcnt lgkmcnt(0)
	v_cvt_pk_bf16_f32 v2, v8, v9
	ds_read2_b32 v[4:5], v69 offset0:82 offset1:115
	s_waitcnt lgkmcnt(0)
	v_cvt_pk_bf16_f32 v3, v4, v5
	ds_read2_b32 v[4:5], v69 offset0:148 offset1:181
	s_waitcnt lgkmcnt(0)
	v_cvt_pk_bf16_f32 v4, v4, v5
	ds_read2_b32 v[8:9], v69 offset0:214 offset1:247
	s_waitcnt lgkmcnt(0)
	v_cvt_pk_bf16_f32 v5, v8, v9
	ds_read2_b32 v[8:9], v69 offset0:20 offset1:53
	global_store_dwordx4 v[10:11], v[2:5], off
	v_mov_b32_e32 v85, v0
	v_lshl_add_u64 v[10:11], v[6:7], 0, v[84:85]
	s_waitcnt lgkmcnt(0)
	v_cvt_pk_bf16_f32 v2, v8, v9
	ds_read2_b32 v[4:5], v69 offset0:86 offset1:119
	s_waitcnt lgkmcnt(0)
	v_cvt_pk_bf16_f32 v3, v4, v5
	ds_read2_b32 v[4:5], v69 offset0:152 offset1:185
	s_waitcnt lgkmcnt(0)
	v_cvt_pk_bf16_f32 v4, v4, v5
	ds_read2_b32 v[8:9], v69 offset0:218 offset1:251
	s_waitcnt lgkmcnt(0)
	v_cvt_pk_bf16_f32 v5, v8, v9
	ds_read2_b32 v[8:9], v69 offset0:24 offset1:57
	global_store_dwordx4 v[10:11], v[2:5], off
	v_mov_b32_e32 v87, v0
	v_lshl_add_u64 v[10:11], v[6:7], 0, v[86:87]
	s_waitcnt lgkmcnt(0)
	v_cvt_pk_bf16_f32 v2, v8, v9
	ds_read2_b32 v[4:5], v69 offset0:90 offset1:123
	s_waitcnt lgkmcnt(0)
	v_cvt_pk_bf16_f32 v3, v4, v5
	ds_read2_b32 v[4:5], v69 offset0:156 offset1:189
	s_waitcnt lgkmcnt(0)
	v_cvt_pk_bf16_f32 v4, v4, v5
	ds_read2_b32 v[8:9], v69 offset0:222 offset1:255
	s_waitcnt lgkmcnt(0)
	v_cvt_pk_bf16_f32 v5, v8, v9
	ds_read2_b32 v[8:9], v69 offset0:28 offset1:61
	global_store_dwordx4 v[10:11], v[2:5], off
	s_waitcnt lgkmcnt(0)
	s_nop 0
	v_cvt_pk_bf16_f32 v2, v8, v9
	ds_read2_b32 v[4:5], v69 offset0:94 offset1:127
	s_waitcnt lgkmcnt(0)
	v_cvt_pk_bf16_f32 v3, v4, v5
	ds_read2_b32 v[4:5], v69 offset0:160 offset1:193
	s_waitcnt lgkmcnt(0)
	v_cvt_pk_bf16_f32 v4, v4, v5
	ds_read2_b32 v[8:9], v89 offset0:98 offset1:131
	v_mov_b32_e32 v89, v0
	v_lshl_add_u64 v[6:7], v[6:7], 0, v[88:89]
	s_waitcnt lgkmcnt(0)
	v_cvt_pk_bf16_f32 v5, v8, v9
	global_store_dwordx4 v[6:7], v[2:5], off
	s_waitcnt lgkmcnt(0)
